# v28 + MLA half-2 head: first K-fragment LDS reads issued before the in-place scale/exp VALU block so their latency overlaps it
# speedup vs baseline: 1.0054x; 1.0054x over previous
.LBB0_549:
	v_cndmask_b32_e64 v165, v165, v202, s[4:5]
	v_mul_f32_e32 v154, 0xbdd53b94, v165
	v_fmamk_f32 v202, v69, 0x3dd53b94, v154
	v_fmamk_f32 v215, v70, 0x3dd53b94, v154
	v_fmamk_f32 v232, v79, 0x3dd53b94, v154
	v_fmamk_f32 v233, v80, 0x3dd53b94, v154
	v_fmamk_f32 v155, v66, 0x3dd53b94, v154
	v_fmamk_f32 v156, v67, 0x3dd53b94, v154
	v_fmamk_f32 v157, v68, 0x3dd53b94, v154
	v_fmamk_f32 v216, v71, 0x3dd53b94, v154
	v_fmamk_f32 v217, v72, 0x3dd53b94, v154
	v_fmamk_f32 v218, v73, 0x3dd53b94, v154
	v_fmamk_f32 v219, v74, 0x3dd53b94, v154
	v_fmamk_f32 v220, v75, 0x3dd53b94, v154
	v_fmamk_f32 v221, v76, 0x3dd53b94, v154
	v_fmamk_f32 v222, v77, 0x3dd53b94, v154
	v_fmamk_f32 v223, v78, 0x3dd53b94, v154
	ds_read_b128 v[66:69], v174 offset:49152
	ds_read_b128 v[70:73], v174 offset:57344
	ds_read_b128 v[146:149], v176 offset:49152
	ds_read_b128 v[150:153], v176 offset:57344
	v_fmamk_f32 v82, v82, 0x3dd53b94, v154
	v_fmamk_f32 v83, v83, 0x3dd53b94, v154
	v_fmamk_f32 v84, v84, 0x3dd53b94, v154
	v_fmamk_f32 v85, v85, 0x3dd53b94, v154
	v_fmamk_f32 v86, v86, 0x3dd53b94, v154
	v_fmamk_f32 v87, v87, 0x3dd53b94, v154
	v_fmamk_f32 v88, v88, 0x3dd53b94, v154
	v_fmamk_f32 v89, v89, 0x3dd53b94, v154
	v_fmamk_f32 v90, v90, 0x3dd53b94, v154
	v_fmamk_f32 v91, v91, 0x3dd53b94, v154
	v_fmamk_f32 v92, v92, 0x3dd53b94, v154
	v_fmamk_f32 v93, v93, 0x3dd53b94, v154
	v_fmamk_f32 v94, v94, 0x3dd53b94, v154
	v_fmamk_f32 v95, v95, 0x3dd53b94, v154
	v_fmamk_f32 v96, v96, 0x3dd53b94, v154
	v_fmamk_f32 v97, v97, 0x3dd53b94, v154
	v_exp_f32_e32 v224, v82
	v_exp_f32_e32 v225, v83
	v_exp_f32_e32 v226, v84
	v_exp_f32_e32 v227, v85
	v_exp_f32_e32 v228, v86
	v_exp_f32_e32 v229, v87
	v_exp_f32_e32 v230, v88
	v_exp_f32_e32 v231, v89
	v_exp_f32_e32 v234, v90
	v_exp_f32_e32 v235, v91
	v_exp_f32_e32 v236, v92
	v_exp_f32_e32 v237, v93
	v_exp_f32_e32 v238, v94
	v_exp_f32_e32 v239, v95
	v_exp_f32_e32 v240, v96
	v_exp_f32_e32 v241, v97
	v_fmac_f32_e32 v154, 0x3dd53b94, v81
	v_exp_f32_e32 v155, v155
	v_exp_f32_e32 v156, v156
	s_waitcnt lgkmcnt(0)
	v_mfma_f32_32x32x16_bf16 v[82:97], v[66:69], v[142:145], 0
	v_exp_f32_e32 v157, v157
	v_exp_f32_e32 v202, v202
	v_exp_f32_e32 v215, v215
	v_exp_f32_e32 v216, v216
	v_exp_f32_e32 v217, v217
	v_exp_f32_e32 v218, v218
	v_exp_f32_e32 v219, v219
	v_mfma_f32_32x32x16_bf16 v[66:81], v[70:73], v[142:145], 0
	v_exp_f32_e32 v220, v220
	v_exp_f32_e32 v221, v221
	v_exp_f32_e32 v222, v222
	v_exp_f32_e32 v223, v223
	v_exp_f32_e32 v242, v232
	v_exp_f32_e32 v243, v233
	v_exp_f32_e32 v244, v154
	v_mfma_f32_32x32x16_bf16 v[82:97], v[146:149], v[138:141], v[82:97]
	v_mfma_f32_32x32x16_bf16 v[66:81], v[150:153], v[138:141], v[66:81]
	ds_read_b128 v[146:149], v178 offset:49152
	ds_read_b128 v[150:153], v178 offset:57344
	s_cmp_lg_u32 s98, 0
	s_cbranch_scc1 .Lattn_mla_nopf
	s_add_u32 s0, s38, s20
	s_addc_u32 s1, s39, s21
	s_add_u32 s100, s0, s42
	s_addc_u32 s101, s1, s43
	s_mov_b32 m0, s93
	v_lshl_add_u64 v[254:255], v[246:247], 0, s[100:101]
	global_load_lds_dwordx4 v[254:255], off
	s_add_u32 s100, s0, s46
	s_addc_u32 s101, s1, s47
	s_mov_b32 m0, s94
	v_lshl_add_u64 v[254:255], v[246:247], 0, s[100:101]
	global_load_lds_dwordx4 v[254:255], off
	s_add_u32 s100, s0, s44
	s_addc_u32 s101, s1, s45
	s_add_i32 s98, s89, s24
	s_mov_b32 m0, s98
	v_lshl_add_u64 v[254:255], v[248:249], 0, s[100:101]
	global_load_lds_dwordx4 v[254:255], off
	s_add_u32 s100, s0, s50
	s_addc_u32 s101, s1, s51
	s_add_i32 m0, s98, 0x2000
	v_lshl_add_u64 v[254:255], v[248:249], 0, s[100:101]
	global_load_lds_dwordx4 v[254:255], off
	s_add_u32 s0, s38, s88
	s_addc_u32 s1, s39, s87
	s_add_u32 s0, s0, s58
	s_addc_u32 s1, s1, s59
	s_mov_b32 m0, s95
	v_lshl_add_u64 v[254:255], v[250:251], 0, s[0:1]
	global_load_lds_dwordx4 v[254:255], off
